# P4 sliding-window task loop: all Q/K fragment loads of a task issued up front with counted waits
# speedup vs baseline: 1.0012x; 1.0012x over previous
; __device__ __forceinline__ int crow(int r, int hi) { return (r & 3) + 8 * (r >> 2) + 4 * hi; }
; #define MFMA32(a, b, c) __builtin_amdgcn_mfma_f32_32x32x16_bf16((a), (b), (c), 0, 0, 0)
; __device__ __forceinline__ void swa_item(int it, LAS unsigned char* lds, const bf16_t* SQ, const bf16_t* SK, const bf16_t* SV, const float* sinks, bf16_t* MIX, int tid, int wid, int lane) {
;     ...
;         bf16x8 qf[4];
; #pragma unroll
;         for (int ks = 0; ks < 4; ++ks) qf[ks] = *(const bf16x8*)(SQ + qrow * 1024 + head * 64 + 16 * ks + 8 * hi);
;         f32x16 st[5];
; #pragma unroll
;         for (int t = 0; t < 5; ++t) {
;             int kp = pos0 + 32 * qt - 128 + 32 * t + x; if (kp < 0) kp = 0;
;             const bf16_t* kptr = SK + (rb + kp) * 128 + kvh * 64 + 8 * hi;
;             f32x16 acc = {};
; #pragma unroll
;             for (int ks = 0; ks < 4; ++ks) acc = MFMA32(*(const bf16x8*)(kptr + 16 * ks), qf[ks], acc);
;             st[t] = acc;
;         }
;         const float sink2 = sinks[head] * LOG2E;
;         float mx = sink2;
; #pragma unroll
;         for (int r = 0; r < 16; ++r) { const int kk = crow(r, hi); if (kk <= x || (n == 0)) st[0][r] = -1e30f; if (kk > x) st[4][r] = -1e30f; }
; #pragma unroll
;         for (int t = 1; t < 4; ++t) if (n == 0 && qt + t < 4) {
; #pragma unroll
;             for (int r = 0; r < 16; ++r) st[t][r] = -1e30f; }
.LBB0_1033:
	global_load_dwordx4 v[66:69], v[118:119], off offset:-64
	global_load_dwordx4 v[176:179], v[118:119], off offset:-32
	global_load_dwordx4 v[180:183], v[118:119], off
	global_load_dwordx4 v[82:85], v[118:119], off offset:32
	global_load_dwordx4 v[34:37], v[108:109], off
	global_load_dwordx4 v[38:41], v[108:109], off offset:32
	global_load_dwordx4 v[42:45], v[108:109], off offset:64
	global_load_dwordx4 v[46:49], v[108:109], off offset:96
	global_load_dwordx4 v[70:73], v[110:111], off
	global_load_dwordx4 v[74:77], v[110:111], off offset:32
	global_load_dwordx4 v[78:81], v[110:111], off offset:64
	global_load_dwordx4 v[184:187], v[110:111], off offset:96
	global_load_dwordx4 v[208:211], v[112:113], off
	global_load_dwordx4 v[212:215], v[112:113], off offset:32
	global_load_dwordx4 v[216:219], v[112:113], off offset:64
	global_load_dwordx4 v[220:223], v[112:113], off offset:96
	global_load_dwordx4 v[224:227], v[114:115], off
	global_load_dwordx4 v[228:231], v[114:115], off offset:32
	global_load_dwordx4 v[232:235], v[114:115], off offset:64
	global_load_dwordx4 v[236:239], v[114:115], off offset:96
	global_load_dwordx4 v[240:243], v[116:117], off
	global_load_dwordx4 v[244:247], v[116:117], off offset:32
	global_load_dwordx4 v[248:251], v[116:117], off offset:64
	s_mov_b32 s14, 0x3fb8aa3b
	s_waitcnt vmcnt(18)
	v_mfma_f32_32x32x16_bf16 v[2:17], v[34:37], v[66:69], 0
	s_nop 0
	s_nop 0
	s_waitcnt vmcnt(17)
	v_mfma_f32_32x32x16_bf16 v[2:17], v[38:41], v[176:179], v[2:17]
	s_nop 0
	s_waitcnt vmcnt(16)
	v_mfma_f32_32x32x16_bf16 v[2:17], v[42:45], v[180:183], v[2:17]
	s_nop 0
	s_waitcnt vmcnt(15)
	v_mfma_f32_32x32x16_bf16 v[2:17], v[46:49], v[82:85], v[2:17]
	s_nop 0
	s_waitcnt vmcnt(14)
	v_mfma_f32_32x32x16_bf16 v[18:33], v[70:73], v[66:69], 0
	s_waitcnt vmcnt(13)
	v_mfma_f32_32x32x16_bf16 v[18:33], v[74:77], v[176:179], v[18:33]
	s_nop 0
	s_waitcnt vmcnt(12)
	v_mfma_f32_32x32x16_bf16 v[18:33], v[78:81], v[180:183], v[18:33]
	s_nop 0
	s_waitcnt vmcnt(11)
	v_mfma_f32_32x32x16_bf16 v[18:33], v[184:187], v[82:85], v[18:33]
	s_nop 0
	s_nop 10
	v_cndmask_b32_e64 v195, v19, v173, s[96:97]
	v_cndmask_b32_e64 v196, v18, v173, s[96:97]
	v_cndmask_b32_e64 v193, v21, v173, s[96:97]
	v_cndmask_b32_e64 v194, v20, v173, s[96:97]
	v_cndmask_b32_e64 v191, v23, v173, s[96:97]
	v_cndmask_b32_e64 v192, v22, v173, s[96:97]
	v_cndmask_b32_e64 v188, v25, v173, s[96:97]
	v_cndmask_b32_e64 v189, v24, v173, s[96:97]
	s_waitcnt vmcnt(10)
	v_mfma_f32_32x32x16_bf16 v[50:65], v[208:211], v[66:69], 0
	global_load_dwordx4 v[208:211], v[116:117], off offset:96
	s_nop 0
	s_waitcnt vmcnt(10)
	v_mfma_f32_32x32x16_bf16 v[50:65], v[212:215], v[176:179], v[50:65]
	s_nop 0
	s_waitcnt vmcnt(9)
	v_mfma_f32_32x32x16_bf16 v[50:65], v[216:219], v[180:183], v[50:65]
	s_nop 0
	s_waitcnt vmcnt(8)
	v_mfma_f32_32x32x16_bf16 v[50:65], v[220:223], v[82:85], v[50:65]
	s_nop 0
	s_nop 10
	v_cndmask_b32_e64 v200, v58, v173, s[0:1]
	v_cndmask_b32_e64 v58, v53, v173, s[0:1]
	v_cndmask_b32_e64 v53, v51, v173, s[0:1]
	v_cndmask_b32_e64 v203, v50, v173, s[0:1]
	v_cndmask_b32_e64 v52, v52, v173, s[0:1]
	v_cndmask_b32_e64 v55, v55, v173, s[0:1]
	v_cndmask_b32_e64 v201, v57, v173, s[0:1]
	v_cndmask_b32_e64 v202, v56, v173, s[0:1]
	v_cndmask_b32_e64 v59, v59, v173, s[0:1]
	v_cndmask_b32_e64 v199, v61, v173, s[0:1]
	v_cndmask_b32_e64 v61, v60, v173, s[0:1]
	v_cndmask_b32_e64 v197, v63, v173, s[0:1]
	v_cndmask_b32_e64 v198, v62, v173, s[0:1]
	s_waitcnt vmcnt(7)
	v_mfma_f32_32x32x16_bf16 v[34:49], v[224:227], v[66:69], 0
	s_waitcnt vmcnt(6)
	v_mfma_f32_32x32x16_bf16 v[34:49], v[228:231], v[176:179], v[34:49]
	s_nop 0
	s_waitcnt vmcnt(5)
	v_mfma_f32_32x32x16_bf16 v[34:49], v[232:235], v[180:183], v[34:49]
	s_nop 0
	s_waitcnt vmcnt(4)
	v_mfma_f32_32x32x16_bf16 v[34:49], v[236:239], v[82:85], v[34:49]
	s_nop 0
	s_nop 10
	v_cndmask_b32_e64 v204, v35, v173, s[6:7]
	v_cndmask_b32_e64 v205, v34, v173, s[6:7]
	v_cndmask_b32_e64 v63, v36, v173, s[6:7]
	v_cndmask_b32_e64 v25, v43, v173, s[6:7]
	v_cndmask_b32_e64 v23, v45, v173, s[6:7]
	v_cndmask_b32_e64 v24, v44, v173, s[6:7]
	v_cndmask_b32_e64 v21, v47, v173, s[6:7]
	v_cndmask_b32_e64 v22, v46, v173, s[6:7]
	v_cndmask_b32_e64 v19, v49, v173, s[6:7]
	v_cndmask_b32_e64 v20, v48, v173, s[6:7]
	s_waitcnt vmcnt(3)
	v_mfma_f32_32x32x16_bf16 v[66:81], v[240:243], v[66:69], 0
	s_waitcnt vmcnt(2)
	v_mfma_f32_32x32x16_bf16 v[66:81], v[244:247], v[176:179], v[66:81]
	s_nop 0
	v_cndmask_b32_e64 v186, v27, v173, s[96:97]
	v_cndmask_b32_e64 v187, v26, v173, s[96:97]
	v_cndmask_b32_e64 v184, v29, v173, s[96:97]
	v_cndmask_b32_e64 v185, v28, v173, s[96:97]
	v_cndmask_b32_e64 v29, v39, v173, s[6:7]
	v_cndmask_b32_e64 v27, v41, v173, s[6:7]
	v_cndmask_b32_e64 v28, v40, v173, s[6:7]
	v_cndmask_b32_e64 v26, v42, v173, s[6:7]
	s_waitcnt vmcnt(1)
	v_mfma_f32_32x32x16_bf16 v[66:81], v[248:251], v[180:183], v[66:81]
	s_nop 0
	v_cndmask_b32_e64 v180, v6, v173, s[72:73]
	v_cndmask_b32_e64 v182, v31, v173, s[96:97]
	v_cndmask_b32_e64 v183, v30, v173, s[96:97]
	v_cndmask_b32_e64 v181, v32, v173, s[96:97]
	v_cndmask_b32_e64 v31, v65, v173, s[0:1]
	v_cndmask_b32_e64 v65, v54, v173, s[0:1]
	v_cndmask_b32_e64 v32, v37, v173, s[6:7]
	v_cndmask_b32_e64 v30, v38, v173, s[6:7]
	s_waitcnt vmcnt(0)
; __device__ __forceinline__ int crow(int r, int hi) { return (r & 3) + 8 * (r >> 2) + 4 * hi; }
; __device__ __forceinline__ void swa_item(int it, LAS unsigned char* lds, const bf16_t* SQ, const bf16_t* SK, const bf16_t* SV, const float* sinks, bf16_t* MIX, int tid, int wid, int lane) {
;     ...
;         const float sink2 = sinks[head] * LOG2E;
;         float mx = sink2;
; #pragma unroll
;         for (int r = 0; r < 16; ++r) { const int kk = crow(r, hi); if (kk <= x || (n == 0)) st[0][r] = -1e30f; if (kk > x) st[4][r] = -1e30f; }
; #pragma unroll
;         for (int t = 1; t < 4; ++t) if (n == 0 && qt + t < 4) {
; #pragma unroll
;             for (int r = 0; r < 16; ++r) st[t][r] = -1e30f; }
; #pragma unroll
;         for (int t = 0; t < 5; ++t)
; #pragma unroll
;             for (int r = 0; r < 16; ++r) mx = fmaxf(mx, st[t][r]);
;         mx = fmaxf(mx, __shfl_xor(mx, 32));
;         float sum = 0.f;
; #pragma unroll
;         for (int t = 0; t < 5; ++t)
; #pragma unroll
;             for (int r = 0; r < 16; ++r) { const float p = __builtin_amdgcn_exp2f(st[t][r] - mx); st[t][r] = p; sum += p; }
;         sum += __shfl_xor(sum, 32); sum += __builtin_amdgcn_exp2f(sink2 - mx);
	v_mfma_f32_32x32x16_bf16 v[66:81], v[208:211], v[82:85], v[66:81]
	global_load_dword v82, v89, s[10:11]
	v_cndmask_b32_e64 v176, v2, v173, s[64:65]
	v_cndmask_b32_e64 v177, v3, v173, s[66:67]
	v_cndmask_b32_e64 v178, v4, v173, s[68:69]
	v_cndmask_b32_e64 v179, v5, v173, s[70:71]
	s_nop 6
	v_cndmask_b32_e64 v2, v66, v173, s[2:3]
	v_cndmask_b32_e64 v175, v2, v66, s[4:5]
	v_cndmask_b32_e64 v66, v73, v173, s[28:29]
	v_cndmask_b32_e64 v73, v10, v173, s[80:81]
	v_cndmask_b32_e64 v83, v69, v173, s[12:13]
	v_cndmask_b32_e64 v69, v70, v173, s[16:17]
	v_cndmask_b32_e64 v70, v7, v173, s[74:75]
	v_cndmask_b32_e64 v85, v173, v67, s[4:5]
	v_cndmask_b32_e64 v84, v68, v173, s[8:9]
	v_cndmask_b32_e64 v68, v71, v173, s[20:21]
	v_cndmask_b32_e64 v71, v8, v173, s[76:77]
	v_cndmask_b32_e64 v67, v72, v173, s[24:25]
	v_cndmask_b32_e64 v72, v9, v173, s[78:79]
	v_cndmask_b32_e64 v9, v74, v173, s[34:35]
	v_cndmask_b32_e64 v74, v11, v173, s[82:83]
	v_cndmask_b32_e64 v8, v75, v173, s[38:39]
	v_cndmask_b32_e64 v75, v12, v173, s[84:85]
	v_cndmask_b32_e64 v7, v76, v173, s[42:43]
	v_cndmask_b32_e64 v76, v13, v173, s[86:87]
	v_cndmask_b32_e64 v6, v77, v173, s[46:47]
	v_cndmask_b32_e64 v77, v14, v173, s[88:89]
	v_cndmask_b32_e64 v5, v78, v173, s[50:51]
	v_cndmask_b32_e64 v78, v15, v173, s[90:91]
	v_cndmask_b32_e64 v4, v79, v173, s[54:55]
	v_cndmask_b32_e64 v79, v16, v173, s[92:93]
	v_cndmask_b32_e64 v3, v80, v173, s[58:59]
	v_cndmask_b32_e64 v80, v17, v173, s[94:95]
	v_cndmask_b32_e64 v2, v81, v173, s[62:63]
	v_cndmask_b32_e64 v81, v33, v173, s[96:97]
	v_cndmask_b32_e64 v33, v64, v173, s[0:1]
	s_waitcnt vmcnt(0)
	v_mul_f32_e32 v10, 0x3fb8aa3b, v82
	v_max3_f32 v10, v10, v176, v177
	v_max3_f32 v10, v10, v178, v179
	v_max3_f32 v10, v10, v180, v70
	v_max3_f32 v10, v10, v71, v72
	v_max3_f32 v10, v10, v73, v74
	v_max3_f32 v10, v10, v75, v76
	v_max3_f32 v10, v10, v77, v78
	v_max3_f32 v10, v10, v79, v80
	v_max3_f32 v10, v10, v196, v195
	v_max3_f32 v10, v10, v194, v193
	v_max3_f32 v10, v10, v192, v191
	v_max3_f32 v10, v10, v189, v188
	v_max3_f32 v10, v10, v187, v186
	v_max3_f32 v10, v10, v185, v184
	v_max3_f32 v10, v10, v183, v182
	v_max3_f32 v10, v10, v181, v81
	v_max3_f32 v10, v10, v203, v53
	v_max3_f32 v10, v10, v52, v58
	v_max3_f32 v10, v10, v65, v55
	v_max3_f32 v10, v10, v202, v201
	v_max3_f32 v10, v10, v200, v59
	v_max3_f32 v10, v10, v61, v199
	v_max3_f32 v10, v10, v198, v197
	v_max3_f32 v10, v10, v33, v31
	v_max3_f32 v10, v10, v205, v204
	v_max3_f32 v10, v10, v63, v32
	v_max3_f32 v10, v10, v30, v29
	v_max3_f32 v10, v10, v28, v27
	v_max3_f32 v10, v10, v26, v25
	v_max3_f32 v10, v10, v24, v23
	v_max3_f32 v10, v10, v22, v21
	v_max3_f32 v10, v10, v20, v19
	v_max3_f32 v10, v10, v175, v85
	v_max3_f32 v10, v10, v84, v83
	v_max3_f32 v10, v10, v69, v68
	v_max3_f32 v10, v10, v67, v66
	v_max3_f32 v10, v10, v9, v8
	v_max3_f32 v10, v10, v7, v6
	v_max3_f32 v10, v10, v5, v4
	v_max3_f32 v10, v10, v3, v2
	ds_bpermute_b32 v11, v174, v10
	s_waitcnt lgkmcnt(0)
	v_max_f32_e32 v11, v11, v11
	v_max_f32_e32 v11, v10, v11
	v_sub_f32_e32 v10, v176, v11
	v_exp_f32_e32 v10, v10
	v_sub_f32_e32 v12, v177, v11
	v_exp_f32_e32 v12, v12
	v_sub_f32_e32 v37, v75, v11
	v_add_f32_e32 v13, 0, v10
	v_exp_f32_e32 v38, v37
	v_add_f32_e32 v14, v12, v13
	v_sub_f32_e32 v13, v178, v11
	v_exp_f32_e32 v13, v13
	v_sub_f32_e32 v37, v76, v11
	v_exp_f32_e32 v40, v37
	v_sub_f32_e32 v37, v77, v11
	v_add_f32_e32 v15, v13, v14
	v_sub_f32_e32 v14, v179, v11
	v_exp_f32_e32 v14, v14
	v_exp_f32_e32 v44, v37
	v_sub_f32_e32 v37, v78, v11
	v_exp_f32_e32 v48, v37
	v_add_f32_e32 v16, v14, v15
	v_sub_f32_e32 v15, v180, v11
	v_exp_f32_e32 v15, v15
	v_sub_f32_e32 v37, v79, v11
	v_exp_f32_e32 v56, v37
	v_sub_f32_e32 v37, v80, v11
	v_add_f32_e32 v17, v15, v16
	v_sub_f32_e32 v16, v70, v11
	v_exp_f32_e32 v16, v16
	v_exp_f32_e32 v60, v37
	v_sub_f32_e32 v41, v194, v11
	v_exp_f32_e32 v42, v41
	v_add_f32_e32 v18, v16, v17
	v_sub_f32_e32 v17, v71, v11
	v_exp_f32_e32 v17, v17
	v_sub_f32_e32 v41, v193, v11
	v_exp_f32_e32 v45, v41
	v_sub_f32_e32 v41, v192, v11
	v_add_f32_e32 v34, v17, v18
	v_sub_f32_e32 v18, v72, v11
	v_exp_f32_e32 v18, v18
	v_exp_f32_e32 v50, v41
	v_sub_f32_e32 v41, v191, v11
	v_exp_f32_e32 v54, v41
	v_add_f32_e32 v35, v18, v34
	v_sub_f32_e32 v34, v73, v11
	v_exp_f32_e32 v34, v34
	v_sub_f32_e32 v41, v189, v11
	v_exp_f32_e32 v64, v41
	v_sub_f32_e32 v41, v188, v11
	v_add_f32_e32 v36, v34, v35
	v_sub_f32_e32 v35, v74, v11
	v_exp_f32_e32 v35, v35
	v_exp_f32_e32 v72, v41
	v_sub_f32_e32 v46, v185, v11
	v_exp_f32_e32 v47, v46
	v_add_f32_e32 v36, v35, v36
	v_add_f32_e32 v36, v38, v36
	v_add_f32_e32 v36, v40, v36
	v_add_f32_e32 v36, v44, v36
	v_add_f32_e32 v36, v48, v36
	v_add_f32_e32 v36, v56, v36
	v_add_f32_e32 v37, v60, v36
	v_sub_f32_e32 v36, v196, v11
	v_exp_f32_e32 v36, v36
	v_sub_f32_e32 v46, v184, v11
	v_exp_f32_e32 v51, v46
	v_sub_f32_e32 v46, v183, v11
	v_add_f32_e32 v39, v36, v37
	v_sub_f32_e32 v37, v195, v11
	v_exp_f32_e32 v37, v37
	v_exp_f32_e32 v57, v46
	v_sub_f32_e32 v46, v182, v11
	v_exp_f32_e32 v62, v46
	v_add_f32_e32 v39, v37, v39
	v_add_f32_e32 v39, v42, v39
	v_add_f32_e32 v39, v45, v39
	v_add_f32_e32 v39, v50, v39
	v_add_f32_e32 v39, v54, v39
	v_add_f32_e32 v39, v64, v39
	v_add_f32_e32 v41, v72, v39
	v_sub_f32_e32 v39, v187, v11
	v_exp_f32_e32 v39, v39
	v_sub_f32_e32 v46, v181, v11
	v_exp_f32_e32 v76, v46
	v_sub_f32_e32 v46, v81, v11
	v_add_f32_e32 v43, v39, v41
	v_sub_f32_e32 v41, v186, v11
	v_exp_f32_e32 v41, v41
	v_exp_f32_e32 v80, v46
	v_sub_f32_e32 v52, v52, v11
	v_sub_f32_e32 v33, v33, v11
	v_add_f32_e32 v43, v41, v43
	v_add_f32_e32 v43, v47, v43
	v_add_f32_e32 v43, v51, v43
	v_add_f32_e32 v43, v57, v43
; #define MFMA32(a, b, c) __builtin_amdgcn_mfma_f32_32x32x16_bf16((a), (b), (c), 0, 0, 0)
; __device__ __forceinline__ void swa_item(int it, LAS unsigned char* lds, const bf16_t* SQ, const bf16_t* SK, const bf16_t* SV, const float* sinks, bf16_t* MIX, int tid, int wid, int lane) {
;     ...
;         float sum = 0.f;
; #pragma unroll
;         for (int t = 0; t < 5; ++t)
; #pragma unroll
;             for (int r = 0; r < 16; ++r) { const float p = __builtin_amdgcn_exp2f(st[t][r] - mx); st[t][r] = p; sum += p; }
;         sum += __shfl_xor(sum, 32); sum += __builtin_amdgcn_exp2f(sink2 - mx);
;         const float inv = 1.0f / sum;
;         f32x16 o0 = {}, o1 = {};
; #pragma unroll
;         for (int t = 0; t < 5; ++t)
; #pragma unroll
;             for (int s = 0; s < 2; ++s) {
;                 const bf16x8 pb = pack8(st[t], s);
;                 const int c0 = 32 * (qt + t) + 16 * s + 4 * hi;
;                 o0 = MFMA32(lds_cat_sw<VS>(VT, x, c0), pb, o0); o1 = MFMA32(lds_cat_sw<VS>(VT, 32 + x, c0), pb, o1);
;                 __builtin_amdgcn_sched_barrier(0);
	v_add_f32_e32 v43, v62, v43
	v_add_f32_e32 v43, v76, v43
	v_add_f32_e32 v46, v80, v43
	v_sub_f32_e32 v43, v203, v11
	v_exp_f32_e32 v43, v43
	v_exp_f32_e32 v182, v33
	v_sub_f32_e32 v31, v31, v11
	v_exp_f32_e32 v184, v31
	v_add_f32_e32 v49, v43, v46
	v_sub_f32_e32 v46, v53, v11
	v_exp_f32_e32 v46, v46
	v_exp_f32_e32 v53, v52
	v_sub_f32_e32 v52, v58, v11
	v_exp_f32_e32 v58, v52
	v_sub_f32_e32 v52, v65, v11
	v_exp_f32_e32 v65, v52
	v_sub_f32_e32 v52, v55, v11
	v_add_f32_e32 v49, v46, v49
	v_exp_f32_e32 v74, v52
	v_sub_f32_e32 v52, v202, v11
	v_add_f32_e32 v49, v53, v49
	v_exp_f32_e32 v177, v52
	v_sub_f32_e32 v52, v201, v11
	v_add_f32_e32 v49, v58, v49
	v_exp_f32_e32 v180, v52
	v_add_f32_e32 v49, v65, v49
	v_add_f32_e32 v49, v74, v49
	v_add_f32_e32 v49, v177, v49
	v_add_f32_e32 v52, v180, v49
	v_sub_f32_e32 v49, v200, v11
	v_exp_f32_e32 v49, v49
	v_sub_f32_e32 v32, v32, v11
	v_exp_f32_e32 v78, v32
	v_sub_f32_e32 v30, v30, v11
	v_add_f32_e32 v55, v49, v52
	v_sub_f32_e32 v52, v59, v11
	v_exp_f32_e32 v52, v52
	v_sub_f32_e32 v59, v61, v11
	v_exp_f32_e32 v61, v59
	v_sub_f32_e32 v59, v199, v11
	v_exp_f32_e32 v70, v59
	v_sub_f32_e32 v59, v198, v11
	v_exp_f32_e32 v77, v59
	v_sub_f32_e32 v59, v197, v11
	v_add_f32_e32 v55, v52, v55
	v_exp_f32_e32 v176, v59
	v_add_f32_e32 v55, v61, v55
	v_add_f32_e32 v55, v70, v55
	v_add_f32_e32 v55, v77, v55
	v_add_f32_e32 v55, v176, v55
	v_add_f32_e32 v33, v182, v55
	v_add_f32_e32 v31, v184, v33
	v_sub_f32_e32 v33, v205, v11
	v_exp_f32_e32 v55, v33
	v_sub_f32_e32 v33, v204, v11
	v_exp_f32_e32 v59, v33
	v_sub_f32_e32 v33, v63, v11
	v_exp_f32_e32 v73, v33
	v_add_f32_e32 v31, v55, v31
	v_exp_f32_e32 v178, v30
	v_sub_f32_e32 v29, v29, v11
	v_add_f32_e32 v31, v59, v31
	v_exp_f32_e32 v181, v29
	v_sub_f32_e32 v28, v28, v11
	v_add_f32_e32 v31, v73, v31
	v_exp_f32_e32 v186, v28
	v_sub_f32_e32 v27, v27, v11
	v_add_f32_e32 v31, v78, v31
	v_exp_f32_e32 v187, v27
	v_sub_f32_e32 v26, v26, v11
	v_add_f32_e32 v30, v178, v31
	v_exp_f32_e32 v63, v26
	v_sub_f32_e32 v25, v25, v11
	v_add_f32_e32 v29, v181, v30
	v_exp_f32_e32 v71, v25
	v_sub_f32_e32 v24, v24, v11
	v_add_f32_e32 v28, v186, v29
	v_exp_f32_e32 v81, v24
	v_sub_f32_e32 v23, v23, v11
	v_add_f32_e32 v27, v187, v28
	v_exp_f32_e32 v179, v23
	v_sub_f32_e32 v22, v22, v11
	v_add_f32_e32 v26, v63, v27
	v_exp_f32_e32 v183, v22
	v_sub_f32_e32 v21, v21, v11
	v_add_f32_e32 v25, v71, v26
	v_exp_f32_e32 v185, v21
	v_sub_f32_e32 v20, v20, v11
	v_add_f32_e32 v24, v81, v25
	v_exp_f32_e32 v189, v20
	v_sub_f32_e32 v19, v19, v11
	v_add_f32_e32 v23, v179, v24
	v_exp_f32_e32 v192, v19
	v_add_f32_e32 v22, v183, v23
	v_add_f32_e32 v21, v185, v22
	v_add_f32_e32 v20, v189, v21
	v_add_f32_e32 v19, v192, v20
	v_sub_f32_e32 v20, v175, v11
	v_exp_f32_e32 v75, v20
	v_sub_f32_e32 v20, v85, v11
	v_exp_f32_e32 v79, v20
	v_sub_f32_e32 v20, v84, v11
	v_exp_f32_e32 v84, v20
	v_sub_f32_e32 v20, v83, v11
	v_exp_f32_e32 v83, v20
	v_sub_f32_e32 v20, v69, v11
	v_add_f32_e32 v19, v75, v19
	v_exp_f32_e32 v85, v20
	v_sub_f32_e32 v20, v68, v11
	v_add_f32_e32 v19, v79, v19
	v_exp_f32_e32 v188, v20
	v_sub_f32_e32 v20, v67, v11
	v_add_f32_e32 v19, v84, v19
	v_exp_f32_e32 v194, v20
	v_sub_f32_e32 v20, v66, v11
	v_add_f32_e32 v19, v83, v19
	v_exp_f32_e32 v195, v20
	v_sub_f32_e32 v9, v9, v11
	v_add_f32_e32 v19, v85, v19
	v_exp_f32_e32 v67, v9
	v_sub_f32_e32 v8, v8, v11
	v_add_f32_e32 v19, v188, v19
	v_exp_f32_e32 v68, v8
	v_sub_f32_e32 v7, v7, v11
	v_add_f32_e32 v19, v194, v19
	v_exp_f32_e32 v69, v7
	v_sub_f32_e32 v6, v6, v11
	v_add_f32_e32 v19, v195, v19
	v_exp_f32_e32 v175, v6
	v_sub_f32_e32 v5, v5, v11
	v_add_f32_e32 v9, v67, v19
	v_exp_f32_e32 v191, v5
	v_sub_f32_e32 v4, v4, v11
	v_add_f32_e32 v8, v68, v9
	v_exp_f32_e32 v193, v4
	v_sub_f32_e32 v3, v3, v11
	v_add_f32_e32 v7, v69, v8
	v_exp_f32_e32 v196, v3
	v_sub_f32_e32 v2, v2, v11
	v_add_f32_e32 v6, v175, v7
	v_exp_f32_e32 v197, v2
	v_add_f32_e32 v5, v191, v6
	v_add_f32_e32 v4, v193, v5
	v_add_f32_e32 v3, v196, v4
	v_add_f32_e32 v2, v197, v3
	ds_bpermute_b32 v3, v174, v2
	v_cvt_pk_bf16_f32 v20, v10, v12
	v_cvt_pk_bf16_f32 v21, v13, v14
	v_cvt_pk_bf16_f32 v22, v15, v16
	v_cvt_pk_bf16_f32 v23, v17, v18
	s_waitcnt lgkmcnt(0)
	v_add_f32_e32 v2, v2, v3
	v_fma_f32 v3, v82, s14, -v11
	v_exp_f32_e32 v3, v3
	s_nop 0
	v_add_f32_e32 v66, v3, v2
	ds_read_b64 v[2:3], v135
	ds_read_b64 v[4:5], v136
	ds_read_b64 v[24:25], v137
	ds_read_b64 v[26:27], v138
	s_waitcnt lgkmcnt(2)
	v_mfma_f32_32x32x16_bf16 v[2:17], v[2:5], v[20:23], 0
	s_waitcnt lgkmcnt(0)
	v_mfma_f32_32x32x16_bf16 v[18:33], v[24:27], v[20:23], 0
	ds_read_b64 v[202:203], v139
	ds_read_b64 v[204:205], v140
	v_cvt_pk_bf16_f32 v198, v34, v35
	v_cvt_pk_bf16_f32 v199, v38, v40
	v_cvt_pk_bf16_f32 v200, v44, v48
	v_cvt_pk_bf16_f32 v201, v56, v60
	s_waitcnt lgkmcnt(0)
	s_nop 0
	v_mfma_f32_32x32x16_bf16 v[2:17], v[202:205], v[198:201], v[2:17]
	ds_read_b64 v[202:203], v141
	ds_read_b64 v[204:205], v142
	s_waitcnt lgkmcnt(0)
	v_mfma_f32_32x32x16_bf16 v[18:33], v[202:205], v[198:201], v[18:33]
	ds_read_b64 v[198:199], v135 offset:64
	ds_read_b64 v[200:201], v143
	v_cvt_pk_bf16_f32 v34, v36, v37
	v_cvt_pk_bf16_f32 v35, v42, v45
	v_cvt_pk_bf16_f32 v36, v50, v54
	v_cvt_pk_bf16_f32 v37, v64, v72
	s_waitcnt lgkmcnt(0)
	s_nop 0
	v_mfma_f32_32x32x16_bf16 v[2:17], v[198:201], v[34:37], v[2:17]
	ds_read_b64 v[198:199], v144
	ds_read_b64 v[200:201], v145
	s_waitcnt lgkmcnt(0)
	v_mfma_f32_32x32x16_bf16 v[18:33], v[198:201], v[34:37], v[18:33]
	v_cvt_pk_bf16_f32 v34, v39, v41
	ds_read_b64 v[38:39], v146
	ds_read_b64 v[40:41], v147
	v_cvt_pk_bf16_f32 v35, v47, v51
	v_cvt_pk_bf16_f32 v36, v57, v62
	v_cvt_pk_bf16_f32 v37, v76, v80
	s_waitcnt lgkmcnt(0)
; __device__ __forceinline__ unsigned cvtpk(float lo, float hi) { f32x2_t v = {lo, hi}; bf16x2_t b = __builtin_convertvector(v, bf16x2_t); return __builtin_bit_cast(unsigned, b); }
; #define MFMA32(a, b, c) __builtin_amdgcn_mfma_f32_32x32x16_bf16((a), (b), (c), 0, 0, 0)
; __device__ __forceinline__ void swa_item(int it, LAS unsigned char* lds, const bf16_t* SQ, const bf16_t* SK, const bf16_t* SV, const float* sinks, bf16_t* MIX, int tid, int wid, int lane) {
;     ...
; #pragma unroll
;         for (int t = 0; t < 5; ++t)
; #pragma unroll
;             for (int s = 0; s < 2; ++s) {
;                 const bf16x8 pb = pack8(st[t], s);
;                 const int c0 = 32 * (qt + t) + 16 * s + 4 * hi;
;                 o0 = MFMA32(lds_cat_sw<VS>(VT, x, c0), pb, o0); o1 = MFMA32(lds_cat_sw<VS>(VT, 32 + x, c0), pb, o1);
;                 __builtin_amdgcn_sched_barrier(0);
;             }
;         bf16_t* op = MIX + qrow * 2048 + 1024 + head * 64 + 4 * hi;
; #pragma unroll
;         for (int g = 0; g < 4; ++g) {
;             u32x2 w0, w1; w0.x = cvtpk(o0[4 * g] * inv, o0[4 * g + 1] * inv); w0.y = cvtpk(o0[4 * g + 2] * inv, o0[4 * g + 3] * inv);
;             w1.x = cvtpk(o1[4 * g] * inv, o1[4 * g + 1] * inv); w1.y = cvtpk(o1[4 * g + 2] * inv, o1[4 * g + 3] * inv);
;             *(u32x2*)(op + 8 * g) = w0; *(u32x2*)(op + 32 + 8 * g) = w1;
;         }
	s_nop 0
	v_mfma_f32_32x32x16_bf16 v[2:17], v[38:41], v[34:37], v[2:17]
	ds_read_b64 v[38:39], v148
	ds_read_b64 v[40:41], v149
	s_waitcnt lgkmcnt(0)
	v_mfma_f32_32x32x16_bf16 v[18:33], v[38:41], v[34:37], v[18:33]
	ds_read_b64 v[38:39], v135 offset:128
	ds_read_b64 v[40:41], v152
	v_cvt_pk_bf16_f32 v34, v43, v46
	v_cvt_pk_bf16_f32 v35, v53, v58
	v_cvt_pk_bf16_f32 v36, v65, v74
	v_cvt_pk_bf16_f32 v37, v177, v180
	s_waitcnt lgkmcnt(0)
	s_nop 0
	v_mfma_f32_32x32x16_bf16 v[2:17], v[38:41], v[34:37], v[2:17]
	ds_read_b64 v[38:39], v153
	ds_read_b64 v[40:41], v154
	s_waitcnt lgkmcnt(0)
	v_mfma_f32_32x32x16_bf16 v[18:33], v[38:41], v[34:37], v[18:33]
	ds_read_b64 v[38:39], v155
	ds_read_b64 v[40:41], v156
	v_cvt_pk_bf16_f32 v34, v49, v52
	v_cvt_pk_bf16_f32 v35, v61, v70
	v_cvt_pk_bf16_f32 v36, v77, v176
	v_cvt_pk_bf16_f32 v37, v182, v184
	s_waitcnt lgkmcnt(0)
	s_nop 0
	v_mfma_f32_32x32x16_bf16 v[2:17], v[38:41], v[34:37], v[2:17]
	ds_read_b64 v[38:39], v157
	ds_read_b64 v[40:41], v158
	s_waitcnt lgkmcnt(0)
	v_mfma_f32_32x32x16_bf16 v[18:33], v[38:41], v[34:37], v[18:33]
	ds_read_b64 v[38:39], v135 offset:192
	ds_read_b64 v[40:41], v159
	v_cvt_pk_bf16_f32 v34, v55, v59
	v_cvt_pk_bf16_f32 v35, v73, v78
	v_cvt_pk_bf16_f32 v36, v178, v181
	v_cvt_pk_bf16_f32 v37, v186, v187
	s_waitcnt lgkmcnt(0)
	s_nop 0
	v_mfma_f32_32x32x16_bf16 v[2:17], v[38:41], v[34:37], v[2:17]
	ds_read_b64 v[38:39], v160
	ds_read_b64 v[40:41], v161
	s_waitcnt lgkmcnt(0)
	v_mfma_f32_32x32x16_bf16 v[18:33], v[38:41], v[34:37], v[18:33]
	ds_read_b64 v[38:39], v162
	ds_read_b64 v[40:41], v163
	v_cvt_pk_bf16_f32 v34, v63, v71
	v_cvt_pk_bf16_f32 v35, v81, v179
	v_cvt_pk_bf16_f32 v36, v183, v185
	v_cvt_pk_bf16_f32 v37, v189, v192
	s_waitcnt lgkmcnt(0)
	s_nop 0
	v_mfma_f32_32x32x16_bf16 v[2:17], v[38:41], v[34:37], v[2:17]
	ds_read_b64 v[38:39], v164
	ds_read_b64 v[40:41], v165
	s_waitcnt lgkmcnt(0)
	v_mfma_f32_32x32x16_bf16 v[18:33], v[38:41], v[34:37], v[18:33]
	ds_read_b64 v[38:39], v135 offset:256
	ds_read_b64 v[40:41], v166
	v_cvt_pk_bf16_f32 v34, v75, v79
	v_cvt_pk_bf16_f32 v35, v84, v83
	v_cvt_pk_bf16_f32 v36, v85, v188
	v_cvt_pk_bf16_f32 v37, v194, v195
	s_waitcnt lgkmcnt(0)
	s_nop 0
	v_mfma_f32_32x32x16_bf16 v[2:17], v[38:41], v[34:37], v[2:17]
	ds_read_b64 v[38:39], v167
	ds_read_b64 v[40:41], v168
	s_waitcnt lgkmcnt(0)
	v_mfma_f32_32x32x16_bf16 v[18:33], v[38:41], v[34:37], v[18:33]
	ds_read_b64 v[38:39], v169
	ds_read_b64 v[40:41], v170
	v_cvt_pk_bf16_f32 v34, v67, v68
	v_cvt_pk_bf16_f32 v35, v69, v175
	v_cvt_pk_bf16_f32 v36, v191, v193
	v_cvt_pk_bf16_f32 v37, v196, v197
	s_waitcnt lgkmcnt(0)
	s_nop 0
	v_mfma_f32_32x32x16_bf16 v[2:17], v[38:41], v[34:37], v[2:17]
	ds_read_b64 v[38:39], v171
	ds_read_b64 v[40:41], v172
	s_waitcnt lgkmcnt(0)
	v_mfma_f32_32x32x16_bf16 v[18:33], v[38:41], v[34:37], v[18:33]
	v_div_scale_f32 v34, s[40:41], v66, v66, 1.0
	v_rcp_f32_e32 v35, v34
	s_add_u32 s10, s10, 8
	s_addc_u32 s11, s11, 0
	v_lshl_add_u64 v[118:119], v[118:119], 0, s[30:31]
	v_fma_f32 v36, -v34, v35, 1.0
	v_fmac_f32_e32 v35, v36, v35
	v_div_scale_f32 v36, vcc, 1.0, v66, 1.0
	v_mul_f32_e32 v37, v36, v35
	v_fma_f32 v38, -v34, v37, v36
	v_fmac_f32_e32 v37, v38, v35
	v_fma_f32 v34, -v34, v37, v36
	v_div_fmas_f32 v34, v34, v35, v37
	v_div_fixup_f32 v34, v34, v66, 1.0
	v_pk_mul_f32 v[2:3], v[2:3], v[34:35] op_sel_hi:[1,0]
	v_pk_mul_f32 v[4:5], v[4:5], v[34:35] op_sel_hi:[1,0]
	v_cvt_pk_bf16_f32 v2, v2, v3
	v_cvt_pk_bf16_f32 v3, v4, v5
	v_pk_mul_f32 v[4:5], v[18:19], v[34:35] op_sel_hi:[1,0]
	v_pk_mul_f32 v[18:19], v[20:21], v[34:35] op_sel_hi:[1,0]
	v_cvt_pk_bf16_f32 v4, v4, v5
	v_cvt_pk_bf16_f32 v5, v18, v19
	global_store_dwordx2 v[120:121], v[2:3], off offset:-64
	global_store_dwordx2 v[120:121], v[4:5], off
	v_pk_mul_f32 v[2:3], v[6:7], v[34:35] op_sel_hi:[1,0]
	v_pk_mul_f32 v[4:5], v[8:9], v[34:35] op_sel_hi:[1,0]
	v_cvt_pk_bf16_f32 v2, v2, v3
	v_cvt_pk_bf16_f32 v3, v4, v5
	v_pk_mul_f32 v[4:5], v[22:23], v[34:35] op_sel_hi:[1,0]
	v_pk_mul_f32 v[6:7], v[24:25], v[34:35] op_sel_hi:[1,0]
	v_cvt_pk_bf16_f32 v4, v4, v5
	v_cvt_pk_bf16_f32 v5, v6, v7
	global_store_dwordx2 v[120:121], v[2:3], off offset:-48
	global_store_dwordx2 v[120:121], v[4:5], off offset:16
	v_pk_mul_f32 v[2:3], v[10:11], v[34:35] op_sel_hi:[1,0]
	v_pk_mul_f32 v[4:5], v[12:13], v[34:35] op_sel_hi:[1,0]
	v_cvt_pk_bf16_f32 v2, v2, v3
	v_cvt_pk_bf16_f32 v3, v4, v5
	v_pk_mul_f32 v[4:5], v[26:27], v[34:35] op_sel_hi:[1,0]
	v_pk_mul_f32 v[6:7], v[28:29], v[34:35] op_sel_hi:[1,0]
	v_cvt_pk_bf16_f32 v4, v4, v5
	v_cvt_pk_bf16_f32 v5, v6, v7
	global_store_dwordx2 v[120:121], v[2:3], off offset:-32
	global_store_dwordx2 v[120:121], v[4:5], off offset:32
	v_pk_mul_f32 v[2:3], v[14:15], v[34:35] op_sel_hi:[1,0]
	v_pk_mul_f32 v[4:5], v[16:17], v[34:35] op_sel_hi:[1,0]
	v_cvt_pk_bf16_f32 v2, v2, v3
	v_cvt_pk_bf16_f32 v3, v4, v5
	v_pk_mul_f32 v[4:5], v[30:31], v[34:35] op_sel_hi:[1,0]
	v_pk_mul_f32 v[6:7], v[32:33], v[34:35] op_sel_hi:[1,0]
	v_add_co_u32_e32 v88, vcc, 8, v88
	v_cvt_pk_bf16_f32 v4, v4, v5
	v_cvt_pk_bf16_f32 v5, v6, v7
	global_store_dwordx2 v[120:121], v[2:3], off offset:-16
	global_store_dwordx2 v[120:121], v[4:5], off offset:48
	v_lshl_add_u64 v[120:121], v[120:121], 0, s[30:31]
	s_and_b64 vcc, exec, vcc
	s_cbranch_vccnz .LBB0_1033
	v_readlane_b32 s64, v254, 36
	v_readlane_b32 s72, v254, 44
	v_readlane_b32 s73, v254, 45
	v_readlane_b32 s74, v254, 46
	v_readlane_b32 s75, v254, 47
	v_readlane_b32 s76, v254, 48
	v_readlane_b32 s77, v254, 49
	v_readlane_b32 s78, v254, 50
	v_readlane_b32 s79, v254, 51
	v_readlane_b32 s88, v255, 38
	v_readlane_b32 s68, v254, 40
	v_readlane_b32 s69, v254, 41
	v_readlane_b32 s70, v254, 42
	v_readlane_b32 s71, v254, 43
	s_mov_b64 s[82:83], s[78:79]
	s_mov_b64 s[96:97], s[52:53]
	v_readlane_b32 s52, v255, 42
	s_mov_b64 s[84:85], s[22:23]
	s_mov_b32 s86, s61
	v_readlane_b32 s89, v255, 39
	s_mov_b32 s87, s26
	s_mov_b64 s[80:81], s[76:77]
	s_mov_b64 s[78:79], s[74:75]
	s_mov_b64 s[76:77], s[72:73]
	s_mov_b64 s[74:75], s[70:71]
	s_mov_b64 s[72:73], s[68:69]
	s_mov_b64 s[94:95], s[36:37]
	s_mov_b64 s[36:37], s[18:19]
	v_readlane_b32 s53, v255, 43
	v_readlane_b32 s90, v255, 40
	v_readlane_b32 s91, v255, 41
	v_readlane_b32 s65, v254, 37
	v_readlane_b32 s66, v254, 38
	v_readlane_b32 s67, v254, 39
	s_branch .LBB0_1022
